# attention main loop: lazy sum-triggered power-of-two rescale replaces per-tile row-max tree
# speedup vs baseline: 1.0116x; 1.0116x over previous
.LBB0_382:
	s_and_b32 s46, s49, 0xc000
	v_add_u32_e32 v238, s46, v199
	ds_read_b64_tr_b16 v[120:121],v238 offset:0
	ds_read_b64_tr_b16 v[122:123],v238 offset:512
	ds_read_b64_tr_b16 v[124:125],v238 offset:4096
	ds_read_b64_tr_b16 v[126:127],v238 offset:4608
	ds_read_b64_tr_b16 v[136:137],v238 offset:8192
	ds_read_b64_tr_b16 v[138:139],v238 offset:8704
	ds_read_b64_tr_b16 v[140:141],v238 offset:12288
	ds_read_b64_tr_b16 v[142:143],v238 offset:12800
	ds_read_b64_tr_b16 v[222:223],v238 offset:1024
	ds_read_b64_tr_b16 v[224:225],v238 offset:1536
	ds_read_b64_tr_b16 v[226:227],v238 offset:5120
	ds_read_b64_tr_b16 v[228:229],v238 offset:5632
	ds_read_b64_tr_b16 v[230:231],v238 offset:9216
	ds_read_b64_tr_b16 v[232:233],v238 offset:9728
	ds_read_b64_tr_b16 v[234:235],v238 offset:13312
	ds_read_b64_tr_b16 v[236:237],v238 offset:13824
	s_waitcnt lgkmcnt(8)
	s_nop 0
	v_mfma_f32_32x32x16_bf16 v[48:63], v[192:195], v[120:123], v[48:63]
	v_exp_f32_e32 v96, v96
	v_exp_f32_e32 v97, v97
	v_add_f32_e32 v239, 0, v96
	v_add_f32_e32 v240, 0, v97
	v_mfma_f32_32x32x16_bf16 v[32:47], v[192:195], v[124:127], v[32:47]
	v_exp_f32_e32 v98, v98
	v_exp_f32_e32 v99, v99
	v_add_f32_e32 v120, v239, v98
	v_add_f32_e32 v121, v240, v99
	v_mfma_f32_32x32x16_bf16 v[16:31], v[192:195], v[136:139], v[16:31]
	v_exp_f32_e32 v100, v100
	v_exp_f32_e32 v101, v101
	v_add_f32_e32 v120, v120, v100
	v_add_f32_e32 v121, v121, v101
	v_mfma_f32_32x32x16_bf16 v[0:15], v[192:195], v[140:143], v[0:15]
	v_exp_f32_e32 v102, v102
	v_exp_f32_e32 v103, v103
	v_add_f32_e32 v239, v120, v102
	v_add_f32_e32 v240, v121, v103
	ds_read_b64_tr_b16 v[120:121],v238 offset:2048
	ds_read_b64_tr_b16 v[122:123],v238 offset:2560
	ds_read_b64_tr_b16 v[124:125],v238 offset:6144
	ds_read_b64_tr_b16 v[126:127],v238 offset:6656
	ds_read_b64_tr_b16 v[136:137],v238 offset:10240
	ds_read_b64_tr_b16 v[138:139],v238 offset:10752
	ds_read_b64_tr_b16 v[140:141],v238 offset:14336
	ds_read_b64_tr_b16 v[142:143],v238 offset:14848
	s_waitcnt lgkmcnt(8)
	v_mfma_f32_32x32x16_bf16 v[48:63], v[132:135], v[222:225], v[48:63]
	v_exp_f32_e32 v104, v104
	v_exp_f32_e32 v105, v105
	v_add_f32_e32 v192, v239, v104
	v_add_f32_e32 v193, v240, v105
	v_mfma_f32_32x32x16_bf16 v[32:47], v[132:135], v[226:229], v[32:47]
	v_exp_f32_e32 v106, v106
	v_exp_f32_e32 v107, v107
	v_add_f32_e32 v192, v192, v106
	v_add_f32_e32 v193, v193, v107
	v_mfma_f32_32x32x16_bf16 v[16:31], v[132:135], v[230:233], v[16:31]
	v_exp_f32_e32 v108, v108
	v_exp_f32_e32 v109, v109
	v_add_f32_e32 v192, v192, v108
	v_add_f32_e32 v193, v193, v109
	v_mfma_f32_32x32x16_bf16 v[0:15], v[132:135], v[234:237], v[0:15]
	v_exp_f32_e32 v110, v110
	v_exp_f32_e32 v111, v111
	v_add_f32_e32 v230, v192, v110
	v_add_f32_e32 v231, v193, v111
	ds_read_b64_tr_b16 v[132:133],v238 offset:3072
	ds_read_b64_tr_b16 v[134:135],v238 offset:3584
	ds_read_b64_tr_b16 v[192:193],v238 offset:7168
	ds_read_b64_tr_b16 v[194:195],v238 offset:7680
	ds_read_b64_tr_b16 v[222:223],v238 offset:11264
	ds_read_b64_tr_b16 v[224:225],v238 offset:11776
	ds_read_b64_tr_b16 v[226:227],v238 offset:15360
	ds_read_b64_tr_b16 v[228:229],v238 offset:15872
	s_waitcnt lgkmcnt(8)
	v_mfma_f32_32x32x16_bf16 v[48:63], v[128:131], v[120:123], v[48:63]
	v_exp_f32_e32 v80, v80
	v_exp_f32_e32 v81, v81
	v_add_f32_e32 v230, v80, v230
	v_add_f32_e32 v231, v81, v231
	v_mfma_f32_32x32x16_bf16 v[32:47], v[128:131], v[124:127], v[32:47]
	v_exp_f32_e32 v82, v82
	v_exp_f32_e32 v83, v83
	v_add_f32_e32 v120, v230, v82
	v_add_f32_e32 v121, v231, v83
	v_mfma_f32_32x32x16_bf16 v[16:31], v[128:131], v[136:139], v[16:31]
	v_exp_f32_e32 v84, v84
	v_exp_f32_e32 v85, v85
	v_add_f32_e32 v120, v120, v84
	v_add_f32_e32 v121, v121, v85
	v_mfma_f32_32x32x16_bf16 v[0:15], v[128:131], v[140:143], v[0:15]
	v_exp_f32_e32 v86, v86
	v_exp_f32_e32 v87, v87
	v_add_f32_e32 v120, v120, v86
	v_add_f32_e32 v121, v121, v87
	s_waitcnt lgkmcnt(0)
	v_mfma_f32_32x32x16_bf16 v[48:63], v[112:115], v[132:135], v[48:63]
	v_exp_f32_e32 v88, v88
	v_exp_f32_e32 v89, v89
	v_add_f32_e32 v120, v120, v88
	v_add_f32_e32 v121, v121, v89
	v_mfma_f32_32x32x16_bf16 v[32:47], v[112:115], v[192:195], v[32:47]
	v_exp_f32_e32 v90, v90
	v_exp_f32_e32 v91, v91
	v_add_f32_e32 v120, v120, v90
	v_add_f32_e32 v121, v121, v91
	v_mfma_f32_32x32x16_bf16 v[16:31], v[112:115], v[222:225], v[16:31]
	v_exp_f32_e32 v92, v92
	v_exp_f32_e32 v93, v93
	v_add_f32_e32 v120, v120, v92
	v_add_f32_e32 v121, v121, v93
	v_mfma_f32_32x32x16_bf16 v[0:15], v[112:115], v[226:229], v[0:15]
	v_exp_f32_e32 v94, v94
	v_exp_f32_e32 v95, v95
	v_add_f32_e32 v192, v120, v94
	v_add_f32_e32 v193, v121, v95
	v_add_f32_e32 v120, v192, v193
	v_cmp_lt_f32_e32 vcc, 0x44800000, v120
	s_cbranch_vccnz .Lattn_rare1

.LBB0_386:
	v_add_f32_e32 v192, v192, v193
	v_add_f32_e32 v192, v203, v192
.LBB0_387:
	s_add_i32 s34, s49, 0xffff4000
	s_and_b32 s34, s34, 0xc000
	v_cvt_pk_bf16_f32 v222, v96, v97
	v_cvt_pk_bf16_f32 v223, v98, v99
	v_cvt_pk_bf16_f32 v224, v100, v101
	v_cvt_pk_bf16_f32 v225, v102, v103
	v_cvt_pk_bf16_f32 v100, v104, v105
	v_cvt_pk_bf16_f32 v101, v106, v107
	v_cvt_pk_bf16_f32 v102, v108, v109
	v_cvt_pk_bf16_f32 v103, v110, v111
	v_cvt_pk_bf16_f32 v96, v80, v81
	v_cvt_pk_bf16_f32 v97, v82, v83
	v_cvt_pk_bf16_f32 v98, v84, v85
	v_cvt_pk_bf16_f32 v99, v86, v87
	v_cvt_pk_bf16_f32 v80, v88, v89
	v_cvt_pk_bf16_f32 v81, v90, v91
	v_cvt_pk_bf16_f32 v82, v92, v93
	v_cvt_pk_bf16_f32 v83, v94, v95
	v_add_u32_e32 v193, s34, v199
	ds_read_b64_tr_b16 v[84:85],v193 offset:0
	ds_read_b64_tr_b16 v[86:87],v193 offset:512
	ds_read_b64_tr_b16 v[88:89],v193 offset:4096
	ds_read_b64_tr_b16 v[90:91],v193 offset:4608
	ds_read_b64_tr_b16 v[92:93],v193 offset:8192
	ds_read_b64_tr_b16 v[94:95],v193 offset:8704
	ds_read_b64_tr_b16 v[104:105],v193 offset:12288
	ds_read_b64_tr_b16 v[106:107],v193 offset:12800
	ds_read_b64_tr_b16 v[108:109],v193 offset:1024
	ds_read_b64_tr_b16 v[110:111],v193 offset:1536
	ds_read_b64_tr_b16 v[226:227],v193 offset:5120
	ds_read_b64_tr_b16 v[228:229],v193 offset:5632
	ds_read_b64_tr_b16 v[230:231],v193 offset:9216
	ds_read_b64_tr_b16 v[232:233],v193 offset:9728
	ds_read_b64_tr_b16 v[234:235],v193 offset:13312
	ds_read_b64_tr_b16 v[236:237],v193 offset:13824
	s_waitcnt lgkmcnt(8)
	s_nop 0
	v_mfma_f32_32x32x16_bf16 v[48:63], v[222:225], v[84:87], v[48:63]
	v_exp_f32_e32 v128, v128
	v_exp_f32_e32 v129, v129
	v_add_f32_e32 v194, 0, v128
	v_add_f32_e32 v195, 0, v129
	v_mfma_f32_32x32x16_bf16 v[32:47], v[222:225], v[88:91], v[32:47]
	v_exp_f32_e32 v130, v130
	v_exp_f32_e32 v131, v131
	v_add_f32_e32 v84, v194, v130
	v_add_f32_e32 v85, v195, v131
	v_mfma_f32_32x32x16_bf16 v[16:31], v[222:225], v[92:95], v[16:31]
	v_exp_f32_e32 v132, v132
	v_exp_f32_e32 v133, v133
	v_add_f32_e32 v84, v84, v132
	v_add_f32_e32 v85, v85, v133
	v_mfma_f32_32x32x16_bf16 v[0:15], v[222:225], v[104:107], v[0:15]
	v_exp_f32_e32 v134, v134
	v_exp_f32_e32 v135, v135
	v_add_f32_e32 v194, v84, v134
	v_add_f32_e32 v195, v85, v135
	ds_read_b64_tr_b16 v[84:85],v193 offset:2048
	ds_read_b64_tr_b16 v[86:87],v193 offset:2560
	ds_read_b64_tr_b16 v[88:89],v193 offset:6144
	ds_read_b64_tr_b16 v[90:91],v193 offset:6656
	ds_read_b64_tr_b16 v[92:93],v193 offset:10240
	ds_read_b64_tr_b16 v[94:95],v193 offset:10752
	ds_read_b64_tr_b16 v[104:105],v193 offset:14336
	ds_read_b64_tr_b16 v[106:107],v193 offset:14848
	s_waitcnt lgkmcnt(8)
	v_mfma_f32_32x32x16_bf16 v[48:63], v[100:103], v[108:111], v[48:63]
	v_exp_f32_e32 v136, v136
	v_exp_f32_e32 v137, v137
	v_add_f32_e32 v194, v194, v136
	v_add_f32_e32 v195, v195, v137
	v_mfma_f32_32x32x16_bf16 v[32:47], v[100:103], v[226:229], v[32:47]
	v_exp_f32_e32 v138, v138
	v_exp_f32_e32 v139, v139
	v_add_f32_e32 v108, v194, v138
	v_add_f32_e32 v109, v195, v139
	v_mfma_f32_32x32x16_bf16 v[16:31], v[100:103], v[230:233], v[16:31]
	v_exp_f32_e32 v140, v140
	v_exp_f32_e32 v141, v141
	v_add_f32_e32 v108, v108, v140
	v_add_f32_e32 v109, v109, v141
	v_mfma_f32_32x32x16_bf16 v[0:15], v[100:103], v[234:237], v[0:15]
	v_exp_f32_e32 v142, v142
	v_exp_f32_e32 v143, v143
	v_add_f32_e32 v194, v108, v142
	v_add_f32_e32 v195, v109, v143
	ds_read_b64_tr_b16 v[100:101],v193 offset:3072
	ds_read_b64_tr_b16 v[102:103],v193 offset:3584
	ds_read_b64_tr_b16 v[108:109],v193 offset:7168
	ds_read_b64_tr_b16 v[110:111],v193 offset:7680
	ds_read_b64_tr_b16 v[222:223],v193 offset:11264
	ds_read_b64_tr_b16 v[224:225],v193 offset:11776
	ds_read_b64_tr_b16 v[226:227],v193 offset:15360
	ds_read_b64_tr_b16 v[228:229],v193 offset:15872
	s_waitcnt lgkmcnt(8)
	v_mfma_f32_32x32x16_bf16 v[48:63], v[96:99], v[84:87], v[48:63]
	v_exp_f32_e32 v112, v112
	v_exp_f32_e32 v113, v113
	v_add_f32_e32 v193, v112, v194
	v_add_f32_e32 v194, v113, v195
	v_mfma_f32_32x32x16_bf16 v[32:47], v[96:99], v[88:91], v[32:47]
	v_exp_f32_e32 v114, v114
	v_exp_f32_e32 v115, v115
	v_add_f32_e32 v84, v193, v114
	v_add_f32_e32 v85, v194, v115
	v_mfma_f32_32x32x16_bf16 v[16:31], v[96:99], v[92:95], v[16:31]
	v_exp_f32_e32 v116, v116
	v_exp_f32_e32 v117, v117
	v_add_f32_e32 v84, v84, v116
	v_add_f32_e32 v85, v85, v117
	v_mfma_f32_32x32x16_bf16 v[0:15], v[96:99], v[104:107], v[0:15]
	v_exp_f32_e32 v118, v118
	v_exp_f32_e32 v119, v119
	v_add_f32_e32 v84, v84, v118
	v_add_f32_e32 v85, v85, v119
	s_waitcnt lgkmcnt(0)
	v_mfma_f32_32x32x16_bf16 v[48:63], v[80:83], v[100:103], v[48:63]
	v_exp_f32_e32 v120, v120
	v_exp_f32_e32 v121, v121
	v_add_f32_e32 v84, v84, v120
	v_add_f32_e32 v85, v85, v121
	v_mfma_f32_32x32x16_bf16 v[32:47], v[80:83], v[108:111], v[32:47]
	v_exp_f32_e32 v122, v122
	v_exp_f32_e32 v123, v123
	v_add_f32_e32 v84, v84, v122
	v_add_f32_e32 v85, v85, v123
	v_mfma_f32_32x32x16_bf16 v[16:31], v[80:83], v[222:225], v[16:31]
	v_exp_f32_e32 v124, v124
	v_exp_f32_e32 v125, v125
	v_add_f32_e32 v84, v84, v124
	v_add_f32_e32 v85, v85, v125
	v_mfma_f32_32x32x16_bf16 v[0:15], v[80:83], v[226:229], v[0:15]
	v_exp_f32_e32 v126, v126
	v_exp_f32_e32 v127, v127
	v_add_f32_e32 v84, v84, v126
	v_add_f32_e32 v85, v85, v127
	v_add_f32_e32 v80, v84, v85
	v_cmp_lt_f32_e32 vcc, 0x44800000, v80
	s_cbranch_vccz .LBB0_380
	v_max3_f32 v86, v128, v129, v130
	v_max3_f32 v87, v131, v132, v133
	v_max3_f32 v86, v86, v134, v135
	v_max3_f32 v87, v87, v136, v137
	v_max3_f32 v86, v86, v138, v139
	v_max3_f32 v87, v87, v140, v141
	v_max3_f32 v86, v86, v142, v143
	v_max3_f32 v87, v87, v112, v113
	v_max3_f32 v86, v86, v114, v115
	v_max3_f32 v87, v87, v116, v117
	v_max3_f32 v86, v86, v118, v119
	v_max3_f32 v87, v87, v120, v121
	v_max3_f32 v86, v86, v122, v123
	v_max3_f32 v87, v87, v124, v125
	v_max3_f32 v86, v86, v126, v127
	v_max_f32_e32 v86, v86, v87
	v_mov_b32_e32 v87, v86
	s_nop 1
	v_permlane32_swap_b32_e32 v86, v87
	v_max_f32_e32 v86, v86, v87
	v_frexp_exp_i32_f32_e32 v87, v86
	v_max_i32_e32 v87, 0, v87
	v_sub_u32_e32 v88, 0, v87
	v_ldexp_f32 v89, 1.0, v88
	v_cvt_f32_i32_e32 v90, v87
	v_add_f32_e32 v202, v202, v90
	v_xor_b32_e32 v64, 0x80000000, v202
	v_mov_b32_e32 v65, v64
	v_mov_b32_e32 v66, v64
	v_mov_b32_e32 v67, v64
	v_mov_b32_e32 v68, v64
	v_mov_b32_e32 v69, v64
	v_mov_b32_e32 v70, v64
	v_mov_b32_e32 v71, v64
	v_mov_b32_e32 v72, v64
	v_mov_b32_e32 v73, v64
	v_mov_b32_e32 v74, v64
	v_mov_b32_e32 v75, v64
	v_mov_b32_e32 v76, v64
	v_mov_b32_e32 v77, v64
	v_mov_b32_e32 v78, v64
	v_mov_b32_e32 v79, v64
	s_and_saveexec_b64 s[44:45], s[4:5]
	ds_write_b32 v218, v89
	s_or_b64 exec, exec, s[44:45]
	v_mul_f32_e32 v128, v128, v89
	v_mul_f32_e32 v129, v129, v89
	v_mul_f32_e32 v130, v130, v89
	v_mul_f32_e32 v131, v131, v89
	v_mul_f32_e32 v132, v132, v89
	v_mul_f32_e32 v133, v133, v89
	v_mul_f32_e32 v134, v134, v89
	v_mul_f32_e32 v135, v135, v89
	v_mul_f32_e32 v136, v136, v89
	v_mul_f32_e32 v137, v137, v89
	v_mul_f32_e32 v138, v138, v89
	v_mul_f32_e32 v139, v139, v89
	v_mul_f32_e32 v140, v140, v89
	v_mul_f32_e32 v141, v141, v89
	v_mul_f32_e32 v142, v142, v89
	v_mul_f32_e32 v143, v143, v89
	v_mul_f32_e32 v112, v112, v89
	v_mul_f32_e32 v113, v113, v89
	v_mul_f32_e32 v114, v114, v89
	v_mul_f32_e32 v115, v115, v89
	v_mul_f32_e32 v116, v116, v89
	v_mul_f32_e32 v117, v117, v89
	v_mul_f32_e32 v118, v118, v89
	v_mul_f32_e32 v119, v119, v89
	v_mul_f32_e32 v120, v120, v89
	v_mul_f32_e32 v121, v121, v89
	v_mul_f32_e32 v122, v122, v89
	v_mul_f32_e32 v123, v123, v89
	v_mul_f32_e32 v124, v124, v89
	v_mul_f32_e32 v125, v125, v89
	v_mul_f32_e32 v126, v126, v89
	v_mul_f32_e32 v127, v127, v89
	v_mul_f32_e32 v84, v84, v89
	v_mul_f32_e32 v85, v85, v89
	v_mul_f32_e32 v192, v192, v89
	s_waitcnt lgkmcnt(0)
	ds_read_b128 v[80:83], v221 offset:96
	ds_read_b128 v[86:89], v221 offset:64
	ds_read_b128 v[90:93], v221 offset:32
	ds_read_b128 v[94:97], v221
	s_waitcnt lgkmcnt(3)
	v_pk_mul_f32 v[60:61], v[60:61], v[80:81]
	s_waitcnt lgkmcnt(2)
	v_pk_mul_f32 v[56:57], v[56:57], v[86:87]
	s_waitcnt lgkmcnt(1)
	v_pk_mul_f32 v[52:53], v[52:53], v[90:91]
	v_pk_mul_f32 v[62:63], v[62:63], v[82:83]
	v_pk_mul_f32 v[58:59], v[58:59], v[88:89]
	v_pk_mul_f32 v[54:55], v[54:55], v[92:93]
	s_waitcnt lgkmcnt(0)
	v_pk_mul_f32 v[50:51], v[50:51], v[96:97]
	v_pk_mul_f32 v[48:49], v[48:49], v[94:95]
	v_pk_mul_f32 v[44:45], v[44:45], v[80:81]
	v_pk_mul_f32 v[40:41], v[40:41], v[86:87]
	v_pk_mul_f32 v[36:37], v[36:37], v[90:91]
	v_pk_mul_f32 v[46:47], v[46:47], v[82:83]
	v_pk_mul_f32 v[42:43], v[42:43], v[88:89]
	v_pk_mul_f32 v[38:39], v[38:39], v[92:93]
	v_pk_mul_f32 v[34:35], v[34:35], v[96:97]
	v_pk_mul_f32 v[32:33], v[32:33], v[94:95]
	v_pk_mul_f32 v[28:29], v[28:29], v[80:81]
	v_pk_mul_f32 v[24:25], v[24:25], v[86:87]
	v_pk_mul_f32 v[20:21], v[20:21], v[90:91]
	v_pk_mul_f32 v[30:31], v[30:31], v[82:83]
	v_pk_mul_f32 v[26:27], v[26:27], v[88:89]
	v_pk_mul_f32 v[22:23], v[22:23], v[92:93]
	v_pk_mul_f32 v[18:19], v[18:19], v[96:97]
	v_pk_mul_f32 v[16:17], v[16:17], v[94:95]
	v_pk_mul_f32 v[12:13], v[12:13], v[80:81]
	v_pk_mul_f32 v[8:9], v[8:9], v[86:87]
	v_pk_mul_f32 v[4:5], v[4:5], v[90:91]
	v_pk_mul_f32 v[14:15], v[14:15], v[82:83]
	v_pk_mul_f32 v[10:11], v[10:11], v[88:89]
	v_pk_mul_f32 v[6:7], v[6:7], v[92:93]
	v_pk_mul_f32 v[2:3], v[2:3], v[96:97]
	v_pk_mul_f32 v[0:1], v[0:1], v[94:95]
	s_branch .LBB0_380
.Lattn_rare1:
	v_max3_f32 v120, v96, v97, v98
	v_max3_f32 v121, v99, v100, v101
	v_max3_f32 v120, v120, v102, v103
	v_max3_f32 v121, v121, v104, v105
	v_max3_f32 v120, v120, v106, v107
	v_max3_f32 v121, v121, v108, v109
	v_max3_f32 v120, v120, v110, v111
	v_max3_f32 v121, v121, v80, v81
	v_max3_f32 v120, v120, v82, v83
	v_max3_f32 v121, v121, v84, v85
	v_max3_f32 v120, v120, v86, v87
	v_max3_f32 v121, v121, v88, v89
	v_max3_f32 v120, v120, v90, v91
	v_max3_f32 v121, v121, v92, v93
	v_max3_f32 v120, v120, v94, v95
	v_max_f32_e32 v120, v120, v121
	v_mov_b32_e32 v121, v120
	s_nop 1
	v_permlane32_swap_b32_e32 v120, v121
	v_max_f32_e32 v120, v120, v121
	v_frexp_exp_i32_f32_e32 v121, v120
	v_max_i32_e32 v121, 0, v121
	v_sub_u32_e32 v122, 0, v121
	v_ldexp_f32 v123, 1.0, v122
	v_cvt_f32_i32_e32 v124, v121
	v_add_f32_e32 v202, v202, v124
	v_xor_b32_e32 v64, 0x80000000, v202
	v_mov_b32_e32 v65, v64
	v_mov_b32_e32 v66, v64
	v_mov_b32_e32 v67, v64
	v_mov_b32_e32 v68, v64
	v_mov_b32_e32 v69, v64
	v_mov_b32_e32 v70, v64
	v_mov_b32_e32 v71, v64
	v_mov_b32_e32 v72, v64
	v_mov_b32_e32 v73, v64
	v_mov_b32_e32 v74, v64
	v_mov_b32_e32 v75, v64
	v_mov_b32_e32 v76, v64
	v_mov_b32_e32 v77, v64
	v_mov_b32_e32 v78, v64
	v_mov_b32_e32 v79, v64
	s_and_saveexec_b64 s[44:45], s[4:5]
	ds_write_b32 v218, v123
	s_or_b64 exec, exec, s[44:45]
	v_mul_f32_e32 v96, v96, v123
	v_mul_f32_e32 v97, v97, v123
	v_mul_f32_e32 v98, v98, v123
	v_mul_f32_e32 v99, v99, v123
	v_mul_f32_e32 v100, v100, v123
	v_mul_f32_e32 v101, v101, v123
	v_mul_f32_e32 v102, v102, v123
	v_mul_f32_e32 v103, v103, v123
	v_mul_f32_e32 v104, v104, v123
	v_mul_f32_e32 v105, v105, v123
	v_mul_f32_e32 v106, v106, v123
	v_mul_f32_e32 v107, v107, v123
	v_mul_f32_e32 v108, v108, v123
	v_mul_f32_e32 v109, v109, v123
	v_mul_f32_e32 v110, v110, v123
	v_mul_f32_e32 v111, v111, v123
	v_mul_f32_e32 v80, v80, v123
	v_mul_f32_e32 v81, v81, v123
	v_mul_f32_e32 v82, v82, v123
	v_mul_f32_e32 v83, v83, v123
	v_mul_f32_e32 v84, v84, v123
	v_mul_f32_e32 v85, v85, v123
	v_mul_f32_e32 v86, v86, v123
	v_mul_f32_e32 v87, v87, v123
	v_mul_f32_e32 v88, v88, v123
	v_mul_f32_e32 v89, v89, v123
	v_mul_f32_e32 v90, v90, v123
	v_mul_f32_e32 v91, v91, v123
	v_mul_f32_e32 v92, v92, v123
	v_mul_f32_e32 v93, v93, v123
	v_mul_f32_e32 v94, v94, v123
	v_mul_f32_e32 v95, v95, v123
	v_mul_f32_e32 v192, v192, v123
	v_mul_f32_e32 v193, v193, v123
	v_mul_f32_e32 v203, v203, v123
	s_waitcnt lgkmcnt(0)
	ds_read_b128 v[112:115], v221 offset:96
	ds_read_b128 v[120:123], v221 offset:64
	ds_read_b128 v[124:127], v221 offset:32
	ds_read_b128 v[128:131], v221
	s_waitcnt lgkmcnt(3)
	v_pk_mul_f32 v[60:61], v[60:61], v[112:113]
	s_waitcnt lgkmcnt(2)
	v_pk_mul_f32 v[56:57], v[56:57], v[120:121]
	s_waitcnt lgkmcnt(1)
	v_pk_mul_f32 v[52:53], v[52:53], v[124:125]
	v_pk_mul_f32 v[62:63], v[62:63], v[114:115]
	v_pk_mul_f32 v[58:59], v[58:59], v[122:123]
	v_pk_mul_f32 v[54:55], v[54:55], v[126:127]
	s_waitcnt lgkmcnt(0)
	v_pk_mul_f32 v[50:51], v[50:51], v[130:131]
	v_pk_mul_f32 v[48:49], v[48:49], v[128:129]
	v_pk_mul_f32 v[44:45], v[44:45], v[112:113]
	v_pk_mul_f32 v[40:41], v[40:41], v[120:121]
	v_pk_mul_f32 v[36:37], v[36:37], v[124:125]
	v_pk_mul_f32 v[46:47], v[46:47], v[114:115]
	v_pk_mul_f32 v[42:43], v[42:43], v[122:123]
	v_pk_mul_f32 v[38:39], v[38:39], v[126:127]
	v_pk_mul_f32 v[34:35], v[34:35], v[130:131]
	v_pk_mul_f32 v[32:33], v[32:33], v[128:129]
	v_pk_mul_f32 v[28:29], v[28:29], v[112:113]
	v_pk_mul_f32 v[24:25], v[24:25], v[120:121]
	v_pk_mul_f32 v[20:21], v[20:21], v[124:125]
	v_pk_mul_f32 v[30:31], v[30:31], v[114:115]
	v_pk_mul_f32 v[26:27], v[26:27], v[122:123]
	v_pk_mul_f32 v[22:23], v[22:23], v[126:127]
	v_pk_mul_f32 v[18:19], v[18:19], v[130:131]
	v_pk_mul_f32 v[16:17], v[16:17], v[128:129]
	v_pk_mul_f32 v[12:13], v[12:13], v[112:113]
	v_pk_mul_f32 v[8:9], v[8:9], v[120:121]
	v_pk_mul_f32 v[4:5], v[4:5], v[124:125]
	v_pk_mul_f32 v[14:15], v[14:15], v[114:115]
	v_pk_mul_f32 v[10:11], v[10:11], v[122:123]
	v_pk_mul_f32 v[6:7], v[6:7], v[126:127]
	v_pk_mul_f32 v[2:3], v[2:3], v[130:131]
	v_pk_mul_f32 v[0:1], v[0:1], v[128:129]
	s_branch .LBB0_384
